# steady attention tile DMAs: SGPR-base form with loop-invariant lane offsets (5 VALU64 adds per step -> SALU), m0 written directly
# baseline (speedup 1.0000x reference)
.LBB0_971:
	s_and_b32 s16, s41, 0x3fffffc0
	s_cmp_lg_u32 0, -1
	v_lshlrev_b32_e32 v3, 1, v52
	s_cselect_b32 s3, 0, 0
	v_lshlrev_b32_e32 v4, 4, v52
	v_and_b32_e32 v3, 32, v3
	s_add_i32 s17, s3, 0x6000
	v_and_b32_e32 v4, 0xc0, v4
	v_add_u32_e32 v54, s17, v3
	v_lshl_or_b32 v55, v221, 8, v4
	v_add_u32_e32 v3, 0, v3
	v_add3_u32 v242, v3, v53, v55
	v_add3_u32 v238, v54, v53, v55
	v_max3_f32 v53, v34, v35, v18
	v_max3_f32 v54, v36, v37, v19
	s_lshl_b32 s16, s16, 2
	v_max3_f32 v53, v53, v20, v21
	v_max3_f32 v54, v54, v40, v41
	s_add_i32 s94, s16, 0
	v_max3_f32 v53, v53, v38, v39
	v_max3_f32 v54, v54, v24, v25
	s_add_i32 s17, s43, 0x100
	v_max3_f32 v53, v53, v22, v23
	v_max3_f32 v54, v54, v44, v45
	s_add_i32 s94, s94, 0x12000
	v_max3_f32 v53, v53, v42, v43
	v_max3_f32 v54, v54, v28, v29
	s_mov_b32 s6, 1
	v_max3_f32 v53, v53, v26, v27
	v_max3_f32 v54, v54, v48, v49
	s_mov_b32 s44, 0
	v_max3_f32 v53, v53, v46, v47
	v_max3_f32 v54, v54, v32, v33
	v_mov_b32_e32 v3, v2
	v_max3_f32 v53, v53, v30, v31
	v_mov_b32_e32 v4, v2
	v_max_f32_e32 v53, v53, v54
	v_mov_b32_e32 v5, v2
	v_mov_b32_e32 v54, v53
	s_nop 1
	v_permlane32_swap_b32_e32 v53, v54
	v_max_f32_e32 v53, v53, v54
	v_mov_b32_e32 v6, v2
	v_add_f32_e32 v240, v225, v53
	v_sub_f32_e32 v18, v18, v53
	v_sub_f32_e32 v19, v19, v53
	v_sub_f32_e32 v34, v34, v53
	v_sub_f32_e32 v35, v35, v53
	v_sub_f32_e32 v36, v36, v53
	s_nop 0
	v_xor_b32_e32 v66, 0x80000000, v240
	v_mov_b32_e32 v67, v66
	v_mov_b32_e32 v68, v66
	v_mov_b32_e32 v69, v66
	v_mov_b32_e32 v70, v66
	v_mov_b32_e32 v71, v66
	v_mov_b32_e32 v72, v66
	v_mov_b32_e32 v73, v66
	v_mov_b32_e32 v74, v66
	v_mov_b32_e32 v75, v66
	v_mov_b32_e32 v76, v66
	v_mov_b32_e32 v77, v66
	v_mov_b32_e32 v78, v66
	v_mov_b32_e32 v79, v66
	v_mov_b32_e32 v80, v66
	v_mov_b32_e32 v81, v66
	s_waitcnt vmcnt(0) lgkmcnt(0)
	s_barrier
	v_exp_f32_e32 v82, v18
	v_exp_f32_e32 v83, v19
	v_lshl_add_u64 v[18:19], v[226:227], 0, s[28:29]
	s_mov_b32 s16, m0
	s_mov_b32 m0, s83
	s_nop 0
	global_load_lds_dwordx4 v[18:19], off
	s_mov_b32 m0, s16
	s_add_i32 s16, s3, s2
	v_lshl_add_u64 v[18:19], v[50:51], 0, s[24:25]
	s_add_i32 s2, s16, 0xa000
	s_mov_b32 s3, m0
	s_mov_b32 m0, s2
	s_nop 0
	global_load_lds_dwordx4 v[18:19], off
	s_mov_b32 m0, s3
	s_mov_b64 s[2:3], 0x10080
	v_lshl_add_u64 v[18:19], v[50:51], 0, s[2:3]
	s_add_i32 s16, s16, 0xc000
	s_mov_b32 s2, m0
	s_mov_b32 m0, s16
	s_nop 0
	global_load_lds_dwordx4 v[18:19], off
	s_mov_b32 m0, s2
	ds_read_b128 v[206:209], v241 offset:8192
	ds_read_b128 v[202:205], v241 offset:8704
	ds_read_b128 v[198:201], v241 offset:10240
	ds_read_b128 v[194:197], v241 offset:10752
	ds_read_b128 v[190:193], v241 offset:12288
	ds_read_b128 v[186:189], v241 offset:12800
	ds_read_b128 v[182:185], v241 offset:14336
	ds_read_b128 v[178:181], v241 offset:14848
	v_sub_f32_e32 v20, v20, v53
	v_sub_f32_e32 v37, v37, v53
	v_sub_f32_e32 v21, v21, v53
	v_sub_f32_e32 v38, v38, v53
	v_sub_f32_e32 v22, v22, v53
	v_sub_f32_e32 v39, v39, v53
	v_sub_f32_e32 v23, v23, v53
	v_sub_f32_e32 v40, v40, v53
	v_sub_f32_e32 v24, v24, v53
	v_sub_f32_e32 v41, v41, v53
	v_sub_f32_e32 v25, v25, v53
	v_sub_f32_e32 v42, v42, v53
	v_sub_f32_e32 v26, v26, v53
	v_sub_f32_e32 v43, v43, v53
	v_sub_f32_e32 v27, v27, v53
	v_sub_f32_e32 v44, v44, v53
	v_sub_f32_e32 v28, v28, v53
	v_sub_f32_e32 v45, v45, v53
	v_sub_f32_e32 v29, v29, v53
	v_sub_f32_e32 v46, v46, v53
	v_sub_f32_e32 v30, v30, v53
	v_sub_f32_e32 v47, v47, v53
	v_sub_f32_e32 v31, v31, v53
	v_sub_f32_e32 v48, v48, v53
	v_sub_f32_e32 v32, v32, v53
	v_sub_f32_e32 v49, v49, v53
	v_sub_f32_e32 v33, v33, v53
	v_exp_f32_e32 v98, v34
	v_exp_f32_e32 v99, v35
	v_exp_f32_e32 v100, v36
	v_exp_f32_e32 v101, v37
	v_exp_f32_e32 v102, v38
	v_exp_f32_e32 v103, v39
	v_exp_f32_e32 v104, v40
	v_exp_f32_e32 v105, v41
	v_exp_f32_e32 v106, v42
	v_exp_f32_e32 v107, v43
	v_exp_f32_e32 v108, v44
	v_exp_f32_e32 v109, v45
	v_exp_f32_e32 v110, v46
	v_exp_f32_e32 v111, v47
	v_exp_f32_e32 v112, v48
	v_exp_f32_e32 v113, v49
	v_exp_f32_e32 v84, v20
	v_exp_f32_e32 v85, v21
	v_exp_f32_e32 v86, v22
	v_exp_f32_e32 v87, v23
	v_exp_f32_e32 v88, v24
	v_exp_f32_e32 v89, v25
	v_exp_f32_e32 v90, v26
	v_exp_f32_e32 v91, v27
	v_exp_f32_e32 v92, v28
	v_exp_f32_e32 v93, v29
	v_exp_f32_e32 v94, v30
	v_exp_f32_e32 v95, v31
	v_exp_f32_e32 v96, v32
	v_exp_f32_e32 v97, v33
	s_waitcnt vmcnt(3) lgkmcnt(0)
	s_barrier
	v_and_b32_e32 v18, 3, v52
	v_mov_b32_e32 v7, v2
	v_mov_b32_e32 v8, v2
	v_mov_b32_e32 v9, v2
	v_mov_b32_e32 v10, v2
	v_mov_b32_e32 v11, v2
	v_mov_b32_e32 v12, v2
	v_mov_b32_e32 v13, v2
	v_mov_b32_e32 v14, v2
	v_mov_b32_e32 v15, v2
	v_mov_b32_e32 v16, v2
	v_mov_b32_e32 v17, v2
	s_lshr_b32 s95, s17, 6
	s_andn2_b64 vcc, exec, s[0:1]
	v_cmp_gt_u32_e64 s[0:1], 32, v223
	v_lshlrev_b32_e32 v243, 4, v221
	v_lshl_add_u32 v237, v234, 2, s94
	v_lshlrev_b32_e32 v224, 4, v18
	s_cbranch_vccnz .LBB0_987
	s_lshl_b32 s2, s41, 8
	s_and_b32 s2, s2, 0xc000
	v_lshl_add_u64 v[18:19], s[4:5], 1, v[224:225]
	v_lshl_or_b32 v20, v220, 10, s2
	v_mov_b32_e32 v21, v225
	v_lshl_add_u64 v[18:19], v[18:19], 0, v[20:21]
	v_lshl_add_u64 v[214:215], s[22:23], 0, v[18:19]
	v_mov_b64_e32 v[64:65], v[16:17]
	v_mov_b64_e32 v[48:49], v[16:17]
	v_mov_b64_e32 v[32:33], v[16:17]
	s_add_i32 s42, s95, -5
	s_movk_i32 s46, 0x2000
	v_add_u32_e32 v228, 0x2000, v238
	s_movk_i32 s44, 0x4000
	s_mov_b32 s2, 0
	v_mov_b32_e32 v244, 0
	s_mov_b64 s[16:17], 0
	v_mov_b64_e32 v[62:63], v[14:15]
	v_mov_b64_e32 v[60:61], v[12:13]
	v_mov_b64_e32 v[58:59], v[10:11]
	v_mov_b64_e32 v[56:57], v[8:9]
	v_mov_b64_e32 v[54:55], v[6:7]
	v_mov_b64_e32 v[52:53], v[4:5]
	v_mov_b64_e32 v[50:51], v[2:3]
	v_mov_b64_e32 v[46:47], v[14:15]
	v_mov_b64_e32 v[44:45], v[12:13]
	v_mov_b64_e32 v[42:43], v[10:11]
	v_mov_b64_e32 v[40:41], v[8:9]
	v_mov_b64_e32 v[38:39], v[6:7]
	v_mov_b64_e32 v[36:37], v[4:5]
	v_mov_b64_e32 v[34:35], v[2:3]
	v_mov_b64_e32 v[30:31], v[14:15]
	v_mov_b64_e32 v[28:29], v[12:13]
	v_mov_b64_e32 v[26:27], v[10:11]
	v_mov_b64_e32 v[24:25], v[8:9]
	v_mov_b64_e32 v[22:23], v[6:7]
	v_mov_b64_e32 v[20:21], v[4:5]
	v_mov_b64_e32 v[18:19], v[2:3]
	v_readfirstlane_b32 s98, v226
	v_readfirstlane_b32 s99, v227
	v_readfirstlane_b32 s100, v214
	v_readfirstlane_b32 s101, v215
	s_nop 1
	v_subrev_u32_e32 v218, s98, v226
	v_subrev_u32_e32 v219, s100, v214
.LBB0_973:
	s_lshl_b32 s40, s2, 1
	v_add_u32_e32 v216, s40, v242
	ds_read_b64_tr_b16 v[210:211], v216 offset:24576
	ds_read_b64_tr_b16 v[212:213], v216 offset:25088
	s_waitcnt lgkmcnt(9)
	v_mfma_f32_32x32x16_bf16 v[130:145], v[206:209], v[174:177], v[66:81]
	v_add_f32_e32 v114, v98, v99
	v_add_f32_e32 v114, v100, v114
	v_add_f32_e32 v114, v101, v114
	v_add_f32_e32 v114, v102, v114
	v_add_f32_e32 v114, v103, v114
	v_cvt_pk_bf16_f32 v158, v98, v99
	v_cvt_pk_bf16_f32 v159, v100, v101
	ds_read_b64_tr_b16 v[206:207], v216 offset:28672
	ds_read_b64_tr_b16 v[208:209], v216 offset:29184
	v_add_f32_e32 v98, v104, v114
	s_waitcnt lgkmcnt(10)
	v_mfma_f32_32x32x16_bf16 v[114:129], v[202:205], v[174:177], v[66:81]
	v_add_f32_e32 v98, v105, v98
	v_add_f32_e32 v98, v106, v98
	v_add_f32_e32 v146, v107, v98
	v_cvt_pk_bf16_f32 v160, v102, v103
	v_cvt_pk_bf16_f32 v161, v104, v105
	ds_read_b64_tr_b16 v[98:99], v216 offset:25600
	ds_read_b64_tr_b16 v[100:101], v216 offset:26112
	s_waitcnt lgkmcnt(11)
	v_mfma_f32_32x32x16_bf16 v[130:145], v[198:201], v[170:173], v[130:145]
	v_add_f32_e32 v102, v108, v146
	v_add_f32_e32 v102, v109, v102
	v_add_f32_e32 v102, v110, v102
	v_add_f32_e32 v146, v111, v102
	v_cvt_pk_bf16_f32 v154, v106, v107
	v_cvt_pk_bf16_f32 v155, v108, v109
	ds_read_b64_tr_b16 v[102:103], v216 offset:29696
	ds_read_b64_tr_b16 v[104:105], v216 offset:30208
	s_waitcnt lgkmcnt(12)
	v_mfma_f32_32x32x16_bf16 v[114:129], v[194:197], v[170:173], v[114:129]
	v_add_f32_e32 v106, v112, v146
	v_add_f32_e32 v106, v113, v106
	v_add_f32_e32 v106, v82, v106
	v_add_f32_e32 v146, v83, v106
	v_cvt_pk_bf16_f32 v156, v110, v111
	v_cvt_pk_bf16_f32 v157, v112, v113
	ds_read_b64_tr_b16 v[106:107], v216 offset:26624
	ds_read_b64_tr_b16 v[108:109], v216 offset:27136
	s_waitcnt lgkmcnt(13)
	v_mfma_f32_32x32x16_bf16 v[130:145], v[190:193], v[166:169], v[130:145]
	v_add_f32_e32 v110, v84, v146
	v_add_f32_e32 v110, v85, v110
	v_add_f32_e32 v110, v86, v110
	v_add_f32_e32 v146, v87, v110
	v_cvt_pk_bf16_f32 v150, v82, v83
	v_cvt_pk_bf16_f32 v151, v84, v85
	ds_read_b64_tr_b16 v[110:111], v216 offset:30720
	ds_read_b64_tr_b16 v[112:113], v216 offset:31232
	s_waitcnt lgkmcnt(14)
	v_mfma_f32_32x32x16_bf16 v[114:129], v[186:189], v[166:169], v[114:129]
	v_add_f32_e32 v82, v88, v146
	v_add_f32_e32 v82, v89, v82
	v_add_f32_e32 v82, v90, v82
	v_add_f32_e32 v82, v91, v82
	v_cvt_pk_bf16_f32 v152, v86, v87
	v_cvt_pk_bf16_f32 v153, v88, v89
	ds_read_b64_tr_b16 v[86:87], v216 offset:27648
	ds_read_b64_tr_b16 v[88:89], v216 offset:28160
	s_waitcnt lgkmcnt(14)
	v_mfma_f32_32x32x16_bf16 v[130:145], v[182:185], v[162:165], v[130:145]
	v_add_f32_e32 v82, v92, v82
	v_add_f32_e32 v82, v93, v82
	v_add_f32_e32 v82, v94, v82
	v_add_f32_e32 v82, v95, v82
	v_cvt_pk_bf16_f32 v146, v90, v91
	v_cvt_pk_bf16_f32 v147, v92, v93
	ds_read_b64_tr_b16 v[90:91], v216 offset:31744
	ds_read_b64_tr_b16 v[92:93], v216 offset:32256
	v_mfma_f32_32x32x16_bf16 v[114:129], v[178:181], v[162:165], v[114:129]
	v_add_f32_e32 v82, v96, v82
	v_add_f32_e32 v82, v97, v82
	v_add_f32_e32 v84, 0, v82
	v_cvt_pk_bf16_f32 v148, v94, v95
	v_cvt_pk_bf16_f32 v149, v96, v97
	s_waitcnt lgkmcnt(14)
	v_mfma_f32_32x32x16_bf16 v[50:65], v[158:161], v[210:213], v[50:65]
	s_add_i32 m0, s46, s83
	s_add_u32 s2, s98, s30
	s_addc_u32 s3, s99, s31
	global_load_lds_dwordx4 v218, s[2:3]
	s_lshl_b32 m0, s44, 1
	s_add_i32 m0, m0, s84
	s_add_u32 s2, s100, s34
	s_addc_u32 s3, s101, s35
	global_load_lds_dwordx4 v219, s[2:3]
	s_waitcnt lgkmcnt(12)
	v_mfma_f32_32x32x16_bf16 v[34:49], v[158:161], v[206:209], v[34:49]
	s_addk_i32 m0, 0x2000
	s_add_u32 s2, s100, s36
	s_addc_u32 s3, s101, s37
	global_load_lds_dwordx4 v219, s[2:3]
	s_waitcnt lgkmcnt(10)
	v_mfma_f32_32x32x16_bf16 v[50:65], v[154:157], v[98:101], v[50:65]
	v_max_f32_e32 v82, v130, v131
	v_max3_f32 v83, v132, v133, v115
	v_max3_f32 v82, v82, v114, v116
	v_max3_f32 v82, v82, v117, v134
	v_max3_f32 v83, v83, v136, v137
	v_max3_f32 v82, v82, v135, v118
	v_max3_f32 v83, v83, v120, v121
	v_max3_f32 v82, v82, v119, v138
	s_waitcnt lgkmcnt(8)
	v_mfma_f32_32x32x16_bf16 v[34:49], v[154:157], v[102:105], v[34:49]
	v_max3_f32 v83, v83, v140, v141
	v_max3_f32 v82, v82, v139, v122
	v_max3_f32 v83, v83, v124, v125
	v_max3_f32 v82, v82, v123, v142
	v_max3_f32 v83, v83, v144, v145
	v_max3_f32 v82, v82, v143, v126
	v_max3_f32 v83, v83, v128, v129
	v_max3_f32 v82, v82, v127, v83
	v_mov_b32_e32 v83, v82
	s_nop 1
	v_permlane32_swap_b32_e32 v82, v83
	v_max_f32_e32 v82, v82, v83
	v_cmp_lt_f32_e32 vcc, s87, v82
	s_cmp_lg_u64 vcc, 0
	v_add_f32_e32 v230, v244, v84
	s_cselect_b64 s[2:3], -1, 0
	s_cbranch_vccnz .LBB0_981

.LBB0_976:
	s_add_i32 s2, s44, 0x2000
	s_cmpk_lg_i32 s44, 0x4000
	s_cselect_b32 s40, s2, 0
	s_lshl_b32 s45, s46, 1
	v_add_u32_e32 v231, s45, v242
	ds_read_b64_tr_b16 v[210:211], v231 offset:24576
	ds_read_b64_tr_b16 v[212:213], v231 offset:25088
	s_waitcnt lgkmcnt(9)
	v_mfma_f32_32x32x16_bf16 v[98:113], v[82:85], v[174:177], v[66:81]
	v_add_f32_e32 v86, v130, v131
	v_add_f32_e32 v86, v132, v86
	v_add_f32_e32 v86, v133, v86
	v_add_f32_e32 v86, v134, v86
	v_add_f32_e32 v86, v135, v86
	v_cvt_pk_bf16_f32 v158, v130, v131
	v_cvt_pk_bf16_f32 v159, v132, v133
	ds_read_b64_tr_b16 v[206:207], v231 offset:28672
	ds_read_b64_tr_b16 v[208:209], v231 offset:29184
	v_add_f32_e32 v82, v136, v86
	v_add_f32_e32 v82, v137, v82
	v_add_f32_e32 v82, v138, v82
	v_add_f32_e32 v146, v139, v82
	s_waitcnt lgkmcnt(10)
	v_mfma_f32_32x32x16_bf16 v[82:97], v[198:201], v[174:177], v[66:81]
	v_cvt_pk_bf16_f32 v160, v134, v135
	v_cvt_pk_bf16_f32 v161, v136, v137
	ds_read_b64_tr_b16 v[130:131], v231 offset:25600
	ds_read_b64_tr_b16 v[132:133], v231 offset:26112
	s_waitcnt lgkmcnt(11)
	v_mfma_f32_32x32x16_bf16 v[98:113], v[202:205], v[170:173], v[98:113]
	v_add_f32_e32 v134, v140, v146
	v_add_f32_e32 v134, v141, v134
	v_add_f32_e32 v134, v142, v134
	v_add_f32_e32 v146, v143, v134
	v_cvt_pk_bf16_f32 v154, v138, v139
	v_cvt_pk_bf16_f32 v155, v140, v141
	ds_read_b64_tr_b16 v[134:135], v231 offset:29696
	ds_read_b64_tr_b16 v[136:137], v231 offset:30208
	s_waitcnt lgkmcnt(12)
	v_mfma_f32_32x32x16_bf16 v[82:97], v[194:197], v[170:173], v[82:97]
	v_add_f32_e32 v138, v144, v146
	v_add_f32_e32 v138, v145, v138
	v_add_f32_e32 v138, v114, v138
	v_add_f32_e32 v146, v115, v138
	v_cvt_pk_bf16_f32 v156, v142, v143
	v_cvt_pk_bf16_f32 v157, v144, v145
	ds_read_b64_tr_b16 v[138:139], v231 offset:26624
	ds_read_b64_tr_b16 v[140:141], v231 offset:27136
	s_waitcnt lgkmcnt(13)
	v_mfma_f32_32x32x16_bf16 v[98:113], v[190:193], v[166:169], v[98:113]
	v_add_f32_e32 v142, v116, v146
	v_add_f32_e32 v142, v117, v142
	v_add_f32_e32 v142, v118, v142
	v_add_f32_e32 v142, v119, v142
	v_cvt_pk_bf16_f32 v150, v114, v115
	v_cvt_pk_bf16_f32 v151, v116, v117
	ds_read_b64_tr_b16 v[114:115], v231 offset:30720
	ds_read_b64_tr_b16 v[116:117], v231 offset:31232
	s_waitcnt lgkmcnt(14)
	v_mfma_f32_32x32x16_bf16 v[82:97], v[186:189], v[166:169], v[82:97]
	v_add_f32_e32 v142, v120, v142
	v_add_f32_e32 v142, v121, v142
	v_add_f32_e32 v142, v122, v142
	v_add_f32_e32 v142, v123, v142
	v_cvt_pk_bf16_f32 v152, v118, v119
	v_cvt_pk_bf16_f32 v153, v120, v121
	ds_read_b64_tr_b16 v[118:119], v231 offset:27648
	ds_read_b64_tr_b16 v[120:121], v231 offset:28160
	s_waitcnt lgkmcnt(14)
	v_mfma_f32_32x32x16_bf16 v[98:113], v[182:185], v[162:165], v[98:113]
	v_add_f32_e32 v142, v124, v142
	v_add_f32_e32 v142, v125, v142
	v_add_f32_e32 v142, v126, v142
	v_add_f32_e32 v142, v127, v142
	v_cvt_pk_bf16_f32 v146, v122, v123
	v_cvt_pk_bf16_f32 v147, v124, v125
	ds_read_b64_tr_b16 v[122:123], v231 offset:31744
	ds_read_b64_tr_b16 v[124:125], v231 offset:32256
	v_mfma_f32_32x32x16_bf16 v[82:97], v[178:181], v[162:165], v[82:97]
	v_add_f32_e32 v142, v128, v142
	v_add_f32_e32 v142, v129, v142
	v_add_f32_e32 v142, 0, v142
	v_cvt_pk_bf16_f32 v148, v126, v127
	v_cvt_pk_bf16_f32 v149, v128, v129
	s_waitcnt lgkmcnt(14)
	v_mfma_f32_32x32x16_bf16 v[50:65], v[158:161], v[210:213], v[50:65]
	s_add_i32 m0, s44, s83
	s_add_u32 s2, s98, 0x50000
	s_addc_u32 s3, s99, 0
	global_load_lds_dwordx4 v218, s[2:3]
	s_lshl_b32 s2, s40, 1
	s_add_i32 s46, s2, s84
	s_mov_b32 m0, s46
	s_add_u32 s2, s100, 0x5830000
	s_addc_u32 s3, s101, 0
	global_load_lds_dwordx4 v219, s[2:3]
	s_waitcnt lgkmcnt(12)
	v_mfma_f32_32x32x16_bf16 v[34:49], v[158:161], v[206:209], v[34:49]
	s_add_i32 m0, s46, 0x2000
	s_add_u32 s2, s100, 0x5830080
	s_addc_u32 s3, s101, 0
	global_load_lds_dwordx4 v219, s[2:3]
	s_waitcnt lgkmcnt(10)
	v_mfma_f32_32x32x16_bf16 v[50:65], v[154:157], v[130:133], v[50:65]
	v_max_f32_e32 v126, v98, v99
	v_max3_f32 v127, v100, v101, v83
	v_max3_f32 v126, v126, v82, v84
	v_max3_f32 v126, v126, v85, v102
	v_max3_f32 v127, v127, v104, v105
	v_max3_f32 v126, v126, v103, v86
	v_max3_f32 v127, v127, v88, v89
	v_max3_f32 v126, v126, v87, v106
	s_waitcnt lgkmcnt(8)
	v_mfma_f32_32x32x16_bf16 v[34:49], v[154:157], v[134:137], v[34:49]
	v_max3_f32 v127, v127, v108, v109
	v_max3_f32 v126, v126, v107, v90
	v_max3_f32 v127, v127, v92, v93
	v_max3_f32 v126, v126, v91, v110
	v_max3_f32 v127, v127, v112, v113
	v_max3_f32 v126, v126, v111, v94
	v_max3_f32 v127, v127, v96, v97
	v_max3_f32 v126, v126, v95, v127
	v_mov_b32_e32 v127, v126
	s_nop 1
	v_permlane32_swap_b32_e32 v126, v127
	v_max_f32_e32 v126, v126, v127
	v_cmp_lt_f32_e32 vcc, s87, v126
	s_cmp_lg_u64 vcc, 0
	v_add_f32_e32 v244, v230, v142
	s_cselect_b64 s[2:3], -1, 0
	s_cbranch_vccnz .LBB0_984

.LBB0_979:
	s_add_i32 s6, s6, 2
	s_add_i32 s2, s40, 0x2000
	s_cmpk_lg_i32 s40, 0x4000
	s_cselect_b32 s45, s2, 0
	s_add_u32 s16, s16, 0x20000
	s_addc_u32 s17, s17, 0
	s_add_u32 s98, s98, 0x20000
	s_addc_u32 s99, s99, 0
	s_add_u32 s100, s100, 0x20000
	s_addc_u32 s101, s101, 0
	s_cmp_ge_i32 s6, s42
	s_cbranch_scc1 .LBB0_988
	s_mov_b32 s2, s44
	s_mov_b32 s46, s40
	s_mov_b32 s44, s45
	s_branch .LBB0_973

.LBB0_1077:
	s_and_b32 s1, s41, 0x3fffffc0
	s_cmp_lg_u32 0, -1
	v_lshlrev_b32_e32 v3, 1, v52
	s_cselect_b32 s0, 0, 0
	v_lshlrev_b32_e32 v4, 4, v52
	v_and_b32_e32 v3, 32, v3
	s_add_i32 s3, s0, 0x6000
	v_and_b32_e32 v4, 0xc0, v4
	v_add_u32_e32 v54, s3, v3
	v_lshl_or_b32 v55, v220, 8, v4
	v_add_u32_e32 v3, 0, v3
	v_add3_u32 v242, v3, v53, v55
	v_add3_u32 v237, v54, v53, v55
	v_max3_f32 v53, v34, v35, v18
	v_max3_f32 v54, v36, v37, v19
	s_lshl_b32 s1, s1, 2
	v_max3_f32 v53, v53, v20, v21
	v_max3_f32 v54, v54, v40, v41
	s_add_i32 s39, s1, 0
	v_max3_f32 v53, v53, v38, v39
	v_max3_f32 v54, v54, v24, v25
	s_add_i32 s2, s0, s2
	v_max3_f32 v53, v53, v22, v23
	v_max3_f32 v54, v54, v44, v45
	s_add_i32 s0, s2, 0xa000
	v_max3_f32 v53, v53, v42, v43
	v_max3_f32 v54, v54, v28, v29
	s_add_i32 s2, s2, 0xc000
	v_max3_f32 v53, v53, v26, v27
	v_max3_f32 v54, v54, v48, v49
	s_add_i32 s39, s39, 0x12000
	v_max3_f32 v53, v53, v46, v47
	v_max3_f32 v54, v54, v32, v33
	s_mov_b32 s8, 1
	v_max3_f32 v53, v53, v30, v31
	s_mov_b32 s43, 0
	v_max_f32_e32 v53, v53, v54
	v_mov_b32_e32 v3, v2
	v_mov_b32_e32 v54, v53
	s_nop 1
	v_permlane32_swap_b32_e32 v53, v54
	v_max_f32_e32 v53, v53, v54
	v_mov_b32_e32 v4, v2
	v_add_f32_e32 v240, v225, v53
	v_sub_f32_e32 v18, v18, v53
	v_sub_f32_e32 v19, v19, v53
	v_sub_f32_e32 v34, v34, v53
	v_sub_f32_e32 v35, v35, v53
	v_sub_f32_e32 v36, v36, v53
	s_nop 0
	v_xor_b32_e32 v66, 0x80000000, v240
	v_mov_b32_e32 v67, v66
	v_mov_b32_e32 v68, v66
	v_mov_b32_e32 v69, v66
	v_mov_b32_e32 v70, v66
	v_mov_b32_e32 v71, v66
	v_mov_b32_e32 v72, v66
	v_mov_b32_e32 v73, v66
	v_mov_b32_e32 v74, v66
	v_mov_b32_e32 v75, v66
	v_mov_b32_e32 v76, v66
	v_mov_b32_e32 v77, v66
	v_mov_b32_e32 v78, v66
	v_mov_b32_e32 v79, v66
	v_mov_b32_e32 v80, v66
	v_mov_b32_e32 v81, v66
	s_waitcnt vmcnt(0) lgkmcnt(0)
	s_barrier
	v_exp_f32_e32 v82, v18
	v_exp_f32_e32 v83, v19
	v_lshl_add_u64 v[18:19], v[226:227], 0, s[20:21]
	s_mov_b32 s1, m0
	s_mov_b32 m0, s44
	s_nop 0
	global_load_lds_dwordx4 v[18:19], off
	s_mov_b32 m0, s1
	v_lshl_add_u64 v[18:19], v[50:51], 0, s[10:11]
	s_mov_b32 s1, m0
	s_mov_b32 m0, s0
	s_nop 0
	global_load_lds_dwordx4 v[18:19], off
	s_mov_b32 m0, s1
	s_mov_b64 s[0:1], 0x10080
	v_lshl_add_u64 v[18:19], v[50:51], 0, s[0:1]
	s_mov_b32 s0, m0
	s_mov_b32 m0, s2
	s_nop 0
	global_load_lds_dwordx4 v[18:19], off
	s_mov_b32 m0, s0
	ds_read_b128 v[206:209], v241 offset:8192
	ds_read_b128 v[198:201], v241 offset:8704
	ds_read_b128 v[202:205], v241 offset:10240
	ds_read_b128 v[194:197], v241 offset:10752
	ds_read_b128 v[190:193], v241 offset:12288
	ds_read_b128 v[186:189], v241 offset:12800
	ds_read_b128 v[182:185], v241 offset:14336
	ds_read_b128 v[178:181], v241 offset:14848
	v_sub_f32_e32 v20, v20, v53
	v_sub_f32_e32 v37, v37, v53
	v_sub_f32_e32 v21, v21, v53
	v_sub_f32_e32 v38, v38, v53
	v_sub_f32_e32 v22, v22, v53
	v_sub_f32_e32 v39, v39, v53
	v_sub_f32_e32 v23, v23, v53
	v_sub_f32_e32 v40, v40, v53
	v_sub_f32_e32 v24, v24, v53
	v_sub_f32_e32 v41, v41, v53
	v_sub_f32_e32 v25, v25, v53
	v_sub_f32_e32 v42, v42, v53
	v_sub_f32_e32 v26, v26, v53
	v_sub_f32_e32 v43, v43, v53
	v_sub_f32_e32 v27, v27, v53
	v_sub_f32_e32 v44, v44, v53
	v_sub_f32_e32 v28, v28, v53
	v_sub_f32_e32 v45, v45, v53
	v_sub_f32_e32 v29, v29, v53
	v_sub_f32_e32 v46, v46, v53
	v_sub_f32_e32 v30, v30, v53
	v_sub_f32_e32 v47, v47, v53
	v_sub_f32_e32 v31, v31, v53
	v_sub_f32_e32 v48, v48, v53
	v_sub_f32_e32 v32, v32, v53
	v_sub_f32_e32 v49, v49, v53
	v_sub_f32_e32 v33, v33, v53
	v_exp_f32_e32 v98, v34
	v_exp_f32_e32 v99, v35
	v_exp_f32_e32 v100, v36
	v_exp_f32_e32 v101, v37
	v_exp_f32_e32 v102, v38
	v_exp_f32_e32 v103, v39
	v_exp_f32_e32 v104, v40
	v_exp_f32_e32 v105, v41
	v_exp_f32_e32 v106, v42
	v_exp_f32_e32 v107, v43
	v_exp_f32_e32 v108, v44
	v_exp_f32_e32 v109, v45
	v_exp_f32_e32 v110, v46
	v_exp_f32_e32 v111, v47
	v_exp_f32_e32 v112, v48
	v_exp_f32_e32 v113, v49
	v_exp_f32_e32 v84, v20
	v_exp_f32_e32 v85, v21
	v_exp_f32_e32 v86, v22
	v_exp_f32_e32 v87, v23
	v_exp_f32_e32 v88, v24
	v_exp_f32_e32 v89, v25
	v_exp_f32_e32 v90, v26
	v_exp_f32_e32 v91, v27
	v_exp_f32_e32 v92, v28
	v_exp_f32_e32 v93, v29
	v_exp_f32_e32 v94, v30
	v_exp_f32_e32 v95, v31
	v_exp_f32_e32 v96, v32
	v_exp_f32_e32 v97, v33
	s_waitcnt vmcnt(3) lgkmcnt(0)
	s_barrier
	v_and_b32_e32 v18, 3, v52
	v_mov_b32_e32 v5, v2
	v_mov_b32_e32 v6, v2
	v_mov_b32_e32 v7, v2
	v_mov_b32_e32 v8, v2
	v_mov_b32_e32 v9, v2
	v_mov_b32_e32 v10, v2
	v_mov_b32_e32 v11, v2
	v_mov_b32_e32 v12, v2
	v_mov_b32_e32 v13, v2
	v_mov_b32_e32 v14, v2
	v_mov_b32_e32 v15, v2
	v_mov_b32_e32 v16, v2
	v_mov_b32_e32 v17, v2
	s_cmp_lt_i32 s46, 7
	v_cmp_gt_u32_e64 s[0:1], 32, v223
	v_lshlrev_b32_e32 v243, 4, v220
	v_lshl_add_u32 v238, v234, 2, s39
	v_lshlrev_b32_e32 v224, 4, v18
	s_cbranch_scc1 .LBB0_1093
	s_add_i32 s42, s46, -5
	s_lshl_b64 s[2:3], s[30:31], 1
	s_add_u32 s2, s2, s16
	s_addc_u32 s3, s3, s17
	s_add_u32 s2, s2, s4
	s_addc_u32 s3, s3, s5
	v_lshl_add_u64 v[18:19], s[2:3], 0, v[224:225]
	s_lshl_b32 s2, s41, 8
	s_and_b32 s2, s2, 0xc000
	v_lshl_or_b32 v20, v221, 10, s2
	v_mov_b32_e32 v21, v225
	v_readlane_b32 s52, v254, 6
	v_lshl_add_u64 v[18:19], v[18:19], 0, v[20:21]
	v_readlane_b32 s58, v254, 12
	v_readlane_b32 s59, v254, 13
	v_mov_b64_e32 v[64:65], v[16:17]
	v_mov_b64_e32 v[48:49], v[16:17]
	v_lshl_add_u64 v[214:215], s[58:59], 0, v[18:19]
	v_mov_b64_e32 v[32:33], v[16:17]
	s_movk_i32 s48, 0x2000
	v_add_u32_e32 v228, 0x2000, v237
	s_movk_i32 s43, 0x4000
	s_mov_b32 s2, 0
	v_mov_b32_e32 v244, 0
	s_mov_b64 s[34:35], 0
	v_mov_b64_e32 v[62:63], v[14:15]
	v_mov_b64_e32 v[60:61], v[12:13]
	v_mov_b64_e32 v[58:59], v[10:11]
	v_mov_b64_e32 v[56:57], v[8:9]
	v_mov_b64_e32 v[54:55], v[6:7]
	v_mov_b64_e32 v[52:53], v[4:5]
	v_mov_b64_e32 v[50:51], v[2:3]
	v_mov_b64_e32 v[46:47], v[14:15]
	v_mov_b64_e32 v[44:45], v[12:13]
	v_mov_b64_e32 v[42:43], v[10:11]
	v_mov_b64_e32 v[40:41], v[8:9]
	v_mov_b64_e32 v[38:39], v[6:7]
	v_mov_b64_e32 v[36:37], v[4:5]
	v_mov_b64_e32 v[34:35], v[2:3]
	v_mov_b64_e32 v[30:31], v[14:15]
	v_mov_b64_e32 v[28:29], v[12:13]
	v_mov_b64_e32 v[26:27], v[10:11]
	v_mov_b64_e32 v[24:25], v[8:9]
	v_mov_b64_e32 v[22:23], v[6:7]
	v_mov_b64_e32 v[20:21], v[4:5]
	v_mov_b64_e32 v[18:19], v[2:3]
	v_readlane_b32 s53, v254, 7
	v_readlane_b32 s54, v254, 8
	v_readlane_b32 s55, v254, 9
	v_readlane_b32 s56, v254, 10
	v_readlane_b32 s57, v254, 11
	v_readfirstlane_b32 s98, v226
	v_readfirstlane_b32 s99, v227
	v_readfirstlane_b32 s100, v214
	v_readfirstlane_b32 s101, v215
	s_nop 1
	v_subrev_u32_e32 v218, s98, v226
	v_subrev_u32_e32 v219, s100, v214
.LBB0_1079:
	s_lshl_b32 s40, s2, 1
	v_add_u32_e32 v216, s40, v242
	ds_read_b64_tr_b16 v[210:211], v216 offset:24576
	ds_read_b64_tr_b16 v[212:213], v216 offset:25088
	s_waitcnt lgkmcnt(9)
	v_mfma_f32_32x32x16_bf16 v[130:145], v[206:209], v[174:177], v[66:81]
	v_add_f32_e32 v114, v98, v99
	v_add_f32_e32 v114, v100, v114
	v_add_f32_e32 v114, v101, v114
	v_add_f32_e32 v114, v102, v114
	v_add_f32_e32 v114, v103, v114
	v_cvt_pk_bf16_f32 v166, v98, v99
	v_cvt_pk_bf16_f32 v167, v100, v101
	ds_read_b64_tr_b16 v[206:207], v216 offset:28672
	ds_read_b64_tr_b16 v[208:209], v216 offset:29184
	v_add_f32_e32 v98, v104, v114
	s_waitcnt lgkmcnt(10)
	v_mfma_f32_32x32x16_bf16 v[114:129], v[198:201], v[174:177], v[66:81]
	v_add_f32_e32 v98, v105, v98
	v_add_f32_e32 v98, v106, v98
	v_add_f32_e32 v154, v107, v98
	v_cvt_pk_bf16_f32 v168, v102, v103
	v_cvt_pk_bf16_f32 v169, v104, v105
	ds_read_b64_tr_b16 v[98:99], v216 offset:25600
	ds_read_b64_tr_b16 v[100:101], v216 offset:26112
	s_waitcnt lgkmcnt(11)
	v_mfma_f32_32x32x16_bf16 v[130:145], v[202:205], v[170:173], v[130:145]
	v_add_f32_e32 v102, v108, v154
	v_add_f32_e32 v102, v109, v102
	v_add_f32_e32 v102, v110, v102
	v_add_f32_e32 v154, v111, v102
	v_cvt_pk_bf16_f32 v162, v106, v107
	v_cvt_pk_bf16_f32 v163, v108, v109
	ds_read_b64_tr_b16 v[102:103], v216 offset:29696
	ds_read_b64_tr_b16 v[104:105], v216 offset:30208
	s_waitcnt lgkmcnt(12)
	v_mfma_f32_32x32x16_bf16 v[114:129], v[194:197], v[170:173], v[114:129]
	v_add_f32_e32 v106, v112, v154
	v_add_f32_e32 v106, v113, v106
	v_add_f32_e32 v106, v82, v106
	v_add_f32_e32 v154, v83, v106
	v_cvt_pk_bf16_f32 v164, v110, v111
	v_cvt_pk_bf16_f32 v165, v112, v113
	ds_read_b64_tr_b16 v[106:107], v216 offset:26624
	ds_read_b64_tr_b16 v[108:109], v216 offset:27136
	s_waitcnt lgkmcnt(13)
	v_mfma_f32_32x32x16_bf16 v[130:145], v[190:193], v[150:153], v[130:145]
	v_add_f32_e32 v110, v84, v154
	v_add_f32_e32 v110, v85, v110
	v_add_f32_e32 v110, v86, v110
	v_add_f32_e32 v154, v87, v110
	v_cvt_pk_bf16_f32 v158, v82, v83
	v_cvt_pk_bf16_f32 v159, v84, v85
	ds_read_b64_tr_b16 v[110:111], v216 offset:30720
	ds_read_b64_tr_b16 v[112:113], v216 offset:31232
	s_waitcnt lgkmcnt(14)
	v_mfma_f32_32x32x16_bf16 v[114:129], v[186:189], v[150:153], v[114:129]
	v_add_f32_e32 v82, v88, v154
	v_add_f32_e32 v82, v89, v82
	v_add_f32_e32 v82, v90, v82
	v_add_f32_e32 v82, v91, v82
	v_cvt_pk_bf16_f32 v160, v86, v87
	v_cvt_pk_bf16_f32 v161, v88, v89
	ds_read_b64_tr_b16 v[86:87], v216 offset:27648
	ds_read_b64_tr_b16 v[88:89], v216 offset:28160
	s_waitcnt lgkmcnt(14)
	v_mfma_f32_32x32x16_bf16 v[130:145], v[182:185], v[146:149], v[130:145]
	v_add_f32_e32 v82, v92, v82
	v_add_f32_e32 v82, v93, v82
	v_add_f32_e32 v82, v94, v82
	v_add_f32_e32 v82, v95, v82
	v_cvt_pk_bf16_f32 v154, v90, v91
	v_cvt_pk_bf16_f32 v155, v92, v93
	ds_read_b64_tr_b16 v[90:91], v216 offset:31744
	ds_read_b64_tr_b16 v[92:93], v216 offset:32256
	v_mfma_f32_32x32x16_bf16 v[114:129], v[178:181], v[146:149], v[114:129]
	v_add_f32_e32 v82, v96, v82
	v_add_f32_e32 v82, v97, v82
	v_add_f32_e32 v84, 0, v82
	v_cvt_pk_bf16_f32 v156, v94, v95
	v_cvt_pk_bf16_f32 v157, v96, v97
	s_waitcnt lgkmcnt(14)
	v_mfma_f32_32x32x16_bf16 v[50:65], v[166:169], v[210:213], v[50:65]
	s_add_i32 m0, s48, s44
	s_add_u32 s2, s98, s22
	s_addc_u32 s3, s99, s23
	global_load_lds_dwordx4 v218, s[2:3]
	s_lshl_b32 m0, s43, 1
	s_add_i32 m0, m0, s45
	s_add_u32 s2, s100, s24
	s_addc_u32 s3, s101, s25
	global_load_lds_dwordx4 v219, s[2:3]
	s_waitcnt lgkmcnt(12)
	v_mfma_f32_32x32x16_bf16 v[34:49], v[166:169], v[206:209], v[34:49]
	s_addk_i32 m0, 0x2000
	s_add_u32 s2, s100, s26
	s_addc_u32 s3, s101, s27
	global_load_lds_dwordx4 v219, s[2:3]
	s_waitcnt lgkmcnt(10)
	v_mfma_f32_32x32x16_bf16 v[50:65], v[162:165], v[98:101], v[50:65]
	v_max_f32_e32 v82, v130, v131
	v_max3_f32 v83, v132, v133, v115
	v_max3_f32 v82, v82, v114, v116
	v_max3_f32 v82, v82, v117, v134
	v_max3_f32 v83, v83, v136, v137
	v_max3_f32 v82, v82, v135, v118
	v_max3_f32 v83, v83, v120, v121
	v_max3_f32 v82, v82, v119, v138
	s_waitcnt lgkmcnt(8)
	v_mfma_f32_32x32x16_bf16 v[34:49], v[162:165], v[102:105], v[34:49]
	v_max3_f32 v83, v83, v140, v141
	v_max3_f32 v82, v82, v139, v122
	v_max3_f32 v83, v83, v124, v125
	v_max3_f32 v82, v82, v123, v142
	v_max3_f32 v83, v83, v144, v145
	v_max3_f32 v82, v82, v143, v126
	v_max3_f32 v83, v83, v128, v129
	v_max3_f32 v82, v82, v127, v83
	v_mov_b32_e32 v83, v82
	s_nop 1
	v_permlane32_swap_b32_e32 v82, v83
	v_max_f32_e32 v82, v82, v83
	v_cmp_lt_f32_e32 vcc, s15, v82
	s_cmp_lg_u64 vcc, 0
	v_add_f32_e32 v230, v244, v84
	s_cselect_b64 s[2:3], -1, 0
	s_cbranch_vccnz .LBB0_1087

.LBB0_1082:
	s_add_i32 s2, s43, 0x2000
	s_cmpk_lg_i32 s43, 0x4000
	s_cselect_b32 s40, s2, 0
	s_lshl_b32 s47, s48, 1
	v_add_u32_e32 v231, s47, v242
	ds_read_b64_tr_b16 v[210:211], v231 offset:24576
	ds_read_b64_tr_b16 v[212:213], v231 offset:25088
	s_waitcnt lgkmcnt(9)
	v_mfma_f32_32x32x16_bf16 v[98:113], v[82:85], v[174:177], v[66:81]
	v_add_f32_e32 v86, v130, v131
	v_add_f32_e32 v86, v132, v86
	v_add_f32_e32 v86, v133, v86
	v_add_f32_e32 v86, v134, v86
	v_add_f32_e32 v86, v135, v86
	v_cvt_pk_bf16_f32 v166, v130, v131
	v_cvt_pk_bf16_f32 v167, v132, v133
	ds_read_b64_tr_b16 v[206:207], v231 offset:28672
	ds_read_b64_tr_b16 v[208:209], v231 offset:29184
	v_add_f32_e32 v82, v136, v86
	v_add_f32_e32 v82, v137, v82
	v_add_f32_e32 v82, v138, v82
	v_add_f32_e32 v154, v139, v82
	s_waitcnt lgkmcnt(10)
	v_mfma_f32_32x32x16_bf16 v[82:97], v[198:201], v[174:177], v[66:81]
	v_cvt_pk_bf16_f32 v168, v134, v135
	v_cvt_pk_bf16_f32 v169, v136, v137
	ds_read_b64_tr_b16 v[130:131], v231 offset:25600
	ds_read_b64_tr_b16 v[132:133], v231 offset:26112
	s_waitcnt lgkmcnt(11)
	v_mfma_f32_32x32x16_bf16 v[98:113], v[202:205], v[170:173], v[98:113]
	v_add_f32_e32 v134, v140, v154
	v_add_f32_e32 v134, v141, v134
	v_add_f32_e32 v134, v142, v134
	v_add_f32_e32 v154, v143, v134
	v_cvt_pk_bf16_f32 v162, v138, v139
	v_cvt_pk_bf16_f32 v163, v140, v141
	ds_read_b64_tr_b16 v[134:135], v231 offset:29696
	ds_read_b64_tr_b16 v[136:137], v231 offset:30208
	s_waitcnt lgkmcnt(12)
	v_mfma_f32_32x32x16_bf16 v[82:97], v[194:197], v[170:173], v[82:97]
	v_add_f32_e32 v138, v144, v154
	v_add_f32_e32 v138, v145, v138
	v_add_f32_e32 v138, v114, v138
	v_add_f32_e32 v154, v115, v138
	v_cvt_pk_bf16_f32 v164, v142, v143
	v_cvt_pk_bf16_f32 v165, v144, v145
	ds_read_b64_tr_b16 v[138:139], v231 offset:26624
	ds_read_b64_tr_b16 v[140:141], v231 offset:27136
	s_waitcnt lgkmcnt(13)
	v_mfma_f32_32x32x16_bf16 v[98:113], v[190:193], v[150:153], v[98:113]
	v_add_f32_e32 v142, v116, v154
	v_add_f32_e32 v142, v117, v142
	v_add_f32_e32 v142, v118, v142
	v_add_f32_e32 v142, v119, v142
	v_cvt_pk_bf16_f32 v158, v114, v115
	v_cvt_pk_bf16_f32 v159, v116, v117
	ds_read_b64_tr_b16 v[114:115], v231 offset:30720
	ds_read_b64_tr_b16 v[116:117], v231 offset:31232
	s_waitcnt lgkmcnt(14)
	v_mfma_f32_32x32x16_bf16 v[82:97], v[186:189], v[150:153], v[82:97]
	v_add_f32_e32 v142, v120, v142
	v_add_f32_e32 v142, v121, v142
	v_add_f32_e32 v142, v122, v142
	v_add_f32_e32 v142, v123, v142
	v_cvt_pk_bf16_f32 v160, v118, v119
	v_cvt_pk_bf16_f32 v161, v120, v121
	ds_read_b64_tr_b16 v[118:119], v231 offset:27648
	ds_read_b64_tr_b16 v[120:121], v231 offset:28160
	s_waitcnt lgkmcnt(14)
	v_mfma_f32_32x32x16_bf16 v[98:113], v[182:185], v[146:149], v[98:113]
	v_add_f32_e32 v142, v124, v142
	v_add_f32_e32 v142, v125, v142
	v_add_f32_e32 v142, v126, v142
	v_add_f32_e32 v142, v127, v142
	v_cvt_pk_bf16_f32 v154, v122, v123
	v_cvt_pk_bf16_f32 v155, v124, v125
	ds_read_b64_tr_b16 v[122:123], v231 offset:31744
	ds_read_b64_tr_b16 v[124:125], v231 offset:32256
	v_mfma_f32_32x32x16_bf16 v[82:97], v[178:181], v[146:149], v[82:97]
	v_add_f32_e32 v142, v128, v142
	v_add_f32_e32 v142, v129, v142
	v_add_f32_e32 v142, 0, v142
	v_cvt_pk_bf16_f32 v156, v126, v127
	v_cvt_pk_bf16_f32 v157, v128, v129
	s_waitcnt lgkmcnt(14)
	v_mfma_f32_32x32x16_bf16 v[50:65], v[166:169], v[210:213], v[50:65]
	s_add_i32 m0, s43, s44
	s_add_u32 s2, s98, 0x50000
	s_addc_u32 s3, s99, 0
	global_load_lds_dwordx4 v218, s[2:3]
	s_lshl_b32 s2, s40, 1
	s_add_i32 s36, s2, s45
	s_mov_b32 m0, s36
	s_add_u32 s2, s100, 0x5830000
	s_addc_u32 s3, s101, 0
	global_load_lds_dwordx4 v219, s[2:3]
	s_waitcnt lgkmcnt(12)
	v_mfma_f32_32x32x16_bf16 v[34:49], v[166:169], v[206:209], v[34:49]
	s_add_i32 m0, s36, 0x2000
	s_add_u32 s2, s100, 0x5830080
	s_addc_u32 s3, s101, 0
	global_load_lds_dwordx4 v219, s[2:3]
	s_waitcnt lgkmcnt(10)
	v_mfma_f32_32x32x16_bf16 v[50:65], v[162:165], v[130:133], v[50:65]
	v_max_f32_e32 v126, v98, v99
	v_max3_f32 v127, v100, v101, v83
	v_max3_f32 v126, v126, v82, v84
	v_max3_f32 v126, v126, v85, v102
	v_max3_f32 v127, v127, v104, v105
	v_max3_f32 v126, v126, v103, v86
	v_max3_f32 v127, v127, v88, v89
	v_max3_f32 v126, v126, v87, v106
	s_waitcnt lgkmcnt(8)
	v_mfma_f32_32x32x16_bf16 v[34:49], v[162:165], v[134:137], v[34:49]
	v_max3_f32 v127, v127, v108, v109
	v_max3_f32 v126, v126, v107, v90
	v_max3_f32 v127, v127, v92, v93
	v_max3_f32 v126, v126, v91, v110
	v_max3_f32 v127, v127, v112, v113
	v_max3_f32 v126, v126, v111, v94
	v_max3_f32 v127, v127, v96, v97
	v_max3_f32 v126, v126, v95, v127
	v_mov_b32_e32 v127, v126
	s_nop 1
	v_permlane32_swap_b32_e32 v126, v127
	v_max_f32_e32 v126, v126, v127
	v_cmp_lt_f32_e32 vcc, s15, v126
	s_cmp_lg_u64 vcc, 0
	v_add_f32_e32 v244, v230, v142
	s_cselect_b64 s[2:3], -1, 0
	s_cbranch_vccnz .LBB0_1090

.LBB0_1085:
	s_add_i32 s8, s8, 2
	s_add_i32 s2, s40, 0x2000
	s_cmpk_lg_i32 s40, 0x4000
	s_cselect_b32 s47, s2, 0
	s_add_u32 s34, s34, 0x20000
	s_addc_u32 s35, s35, 0
	s_add_u32 s98, s98, 0x20000
	s_addc_u32 s99, s99, 0
	s_add_u32 s100, s100, 0x20000
	s_addc_u32 s101, s101, 0
	s_cmp_ge_i32 s8, s42
	s_cbranch_scc1 .LBB0_1094
	s_mov_b32 s2, s43
	s_mov_b32 s48, s40
	s_mov_b32 s43, s47
	s_branch .LBB0_1079
